# v73 + P0 xn pass: 64-lane sum-of-squares reductions by DPP (quad_perm/row_mirror/row_bcast, bit-identical order) instead of six dependent ds_bpermute round trips
# speedup vs baseline: 1.0195x; 1.0031x over previous
.LBB0_104:
	s_add_i32 s9, s4, s62
	s_cmp_lt_i32 s9, 0x8400
	s_cselect_b32 s2, s9, s4
	s_add_i32 s0, s4, 0xffff8000
	s_ashr_i32 s5, s4, 31
	s_cmp_lt_i32 s4, 0x8000
	v_readlane_b32 s12, v254, 0
	s_cselect_b32 s1, s5, 0
	s_cselect_b32 s0, s4, s0
	v_readlane_b32 s13, v254, 1
	v_readlane_b32 s14, v254, 2
	v_readlane_b32 s15, v254, 3
	s_cselect_b32 s3, s13, s15
	s_cselect_b32 s10, s12, s14
	s_lshl_b64 s[0:1], s[0:1], 12
	s_add_u32 s0, s10, s0
	s_addc_u32 s1, s3, s1
	v_lshl_add_u64 v[16:17], s[0:1], 0, v[52:53]
	global_load_dwordx4 v[44:47], v[16:17], off nt
	global_load_dwordx4 v[40:43], v[16:17], off offset:16 nt
	global_load_dwordx4 v[32:35], v[16:17], off offset:2064 nt
	global_load_dwordx4 v[36:39], v[16:17], off offset:2048 nt
	s_add_i32 s0, s2, 0xffff8000
	s_ashr_i32 s3, s2, 31
	s_cmp_lt_i32 s2, 0x8000
	s_cselect_b32 s1, s3, 0
	s_cselect_b32 s0, s2, s0
	s_cselect_b32 s10, s13, s15
	s_cselect_b32 s11, s12, s14
	s_lshl_b64 s[0:1], s[0:1], 12
	s_add_u32 s0, s11, s0
	s_addc_u32 s1, s10, s1
	v_lshl_add_u64 v[20:21], s[0:1], 0, v[52:53]
	global_load_dwordx4 v[24:27], v[20:21], off offset:16 nt
	global_load_dwordx4 v[28:31], v[20:21], off nt
	global_load_dwordx4 v[16:19], v[20:21], off offset:2064 nt
	s_nop 0
	global_load_dwordx4 v[20:23], v[20:21], off offset:2048 nt
	v_readlane_b32 s16, v254, 4
	v_readlane_b32 s17, v254, 5
	v_readlane_b32 s18, v254, 6
	v_readlane_b32 s19, v254, 7
	v_readlane_b32 s20, v254, 8
	v_readlane_b32 s21, v254, 9
	v_readlane_b32 s22, v254, 10
	v_readlane_b32 s23, v254, 11
	v_readlane_b32 s24, v254, 12
	v_readlane_b32 s25, v254, 13
	v_readlane_b32 s26, v254, 14
	v_readlane_b32 s27, v254, 15
	s_waitcnt vmcnt(7)
	v_pk_mul_f32 v[62:63], v[46:47], v[46:47]
	v_pk_mul_f32 v[64:65], v[44:45], v[44:45]
	s_waitcnt vmcnt(6)
	v_pk_mul_f32 v[66:67], v[42:43], v[42:43]
	v_pk_mul_f32 v[68:69], v[40:41], v[40:41]
	v_pk_mov_b32 v[72:73], v[64:65], v[62:63] op_sel:[1,0]
	v_mov_b32_e32 v65, v63
	v_pk_mov_b32 v[62:63], v[68:69], v[66:67] op_sel:[1,0]
	v_mov_b32_e32 v69, v67
	s_waitcnt vmcnt(4)
	v_mul_f32_e32 v48, v37, v37
	v_mul_f32_e32 v70, v39, v39
	v_pk_add_f32 v[64:65], v[72:73], v[64:65]
	v_pk_add_f32 v[62:63], v[62:63], v[68:69]
	v_mul_f32_e32 v61, v32, v32
	v_mul_f32_e32 v74, v33, v33
	v_mul_f32_e32 v75, v34, v34
	v_mul_f32_e32 v76, v35, v35
	v_pk_fma_f32 v[66:67], v[36:37], v[36:37], v[48:49] op_sel_hi:[1,1,0]
	v_pk_fma_f32 v[70:71], v[38:39], v[38:39], v[70:71] op_sel_hi:[1,1,0]
	v_pk_add_f32 v[64:65], v[64:65], v[64:65] op_sel:[0,1] op_sel_hi:[1,0]
	v_pk_add_f32 v[62:63], v[62:63], v[62:63] op_sel:[0,1] op_sel_hi:[1,0]
	v_mov_b32_e32 v67, v75
	v_mov_b32_e32 v71, v76
	v_mov_b32_e32 v65, v61
	v_mov_b32_e32 v63, v74
	v_pk_add_f32 v[66:67], v[66:67], v[70:71]
	v_pk_add_f32 v[62:63], v[64:65], v[62:63]
	s_nop 0
	v_pk_add_f32 v[62:63], v[62:63], v[66:67]
	s_nop 0
	v_add_f32_e32 v48, v62, v63
	s_nop 1
	v_add_f32_dpp v48, v48, v48 quad_perm:[1,0,3,2] row_mask:0xf bank_mask:0xf
	s_nop 1
	v_add_f32_dpp v48, v48, v48 quad_perm:[2,3,0,1] row_mask:0xf bank_mask:0xf
	s_nop 1
	v_add_f32_dpp v48, v48, v48 row_half_mirror row_mask:0xf bank_mask:0xf
	s_nop 1
	v_add_f32_dpp v48, v48, v48 row_mirror row_mask:0xf bank_mask:0xf
	s_nop 1
	v_add_f32_dpp v48, v48, v48 row_bcast:15 row_mask:0xa bank_mask:0xf
	s_nop 1
	v_add_f32_dpp v48, v48, v48 row_bcast:31 row_mask:0xc bank_mask:0xf
	s_nop 1
	v_readlane_b32 s98, v48, 63
	s_nop 1
	v_mov_b32_e32 v48, s98
	v_fmamk_f32 v48, v48, 0x3a800000, v60
	v_mul_f32_e32 v61, 0x4b800000, v48
	v_cmp_gt_f32_e64 s[0:1], s8, v48
	s_nop 1
	v_cndmask_b32_e64 v48, v48, v61, s[0:1]
	v_rsq_f32_e32 v48, v48
	s_nop 0
	v_mul_f32_e32 v61, 0x45800000, v48
	v_cndmask_b32_e64 v48, v48, v61, s[0:1]
	s_and_saveexec_b64 s[0:1], vcc
	s_cbranch_execz .LBB0_106
	s_lshl_b64 s[10:11], s[4:5], 2
	s_add_u32 s10, s6, s10
	s_addc_u32 s11, s7, s11
	global_store_dword v49, v48, s[10:11]
.LBB0_106:
	s_or_b64 exec, exec, s[0:1]
	s_waitcnt vmcnt(2)
	v_pk_mul_f32 v[62:63], v[30:31], v[30:31]
	v_pk_mul_f32 v[64:65], v[28:29], v[28:29]
	s_waitcnt vmcnt(1)
	v_mul_f32_e32 v61, v16, v16
	v_pk_mov_b32 v[66:67], v[64:65], v[62:63] op_sel:[1,0]
	v_mov_b32_e32 v65, v63
	v_pk_add_f32 v[62:63], v[66:67], v[64:65]
	v_pk_mul_f32 v[64:65], v[26:27], v[26:27]
	v_pk_mul_f32 v[66:67], v[24:25], v[24:25]
	v_pk_add_f32 v[62:63], v[62:63], v[62:63] op_sel:[0,1] op_sel_hi:[1,0]
	v_pk_mov_b32 v[68:69], v[66:67], v[64:65] op_sel:[1,0]
	v_mov_b32_e32 v67, v65
	v_pk_add_f32 v[64:65], v[68:69], v[66:67]
	v_mul_f32_e32 v66, v17, v17
	v_pk_add_f32 v[64:65], v[64:65], v[64:65] op_sel:[0,1] op_sel_hi:[1,0]
	v_mov_b32_e32 v63, v61
	v_mov_b32_e32 v65, v66
	v_pk_add_f32 v[62:63], v[62:63], v[64:65]
	s_waitcnt vmcnt(0)
	v_mul_f32_e32 v64, v21, v21
	v_mul_f32_e32 v67, v18, v18
	v_pk_fma_f32 v[64:65], v[20:21], v[20:21], v[64:65] op_sel_hi:[1,1,0]
	v_mul_f32_e32 v66, v23, v23
	v_mul_f32_e32 v68, v19, v19
	v_mov_b32_e32 v65, v67
	v_pk_fma_f32 v[66:67], v[22:23], v[22:23], v[66:67] op_sel_hi:[1,1,0]
	v_pk_mul_f32 v[44:45], v[44:45], v[48:49] op_sel_hi:[1,0]
	v_mov_b32_e32 v67, v68
	v_pk_add_f32 v[64:65], v[64:65], v[66:67]
	v_pk_mul_f32 v[44:45], v[4:5], v[44:45]
	v_pk_add_f32 v[62:63], v[62:63], v[64:65]
	v_pk_mul_f32 v[42:43], v[42:43], v[48:49] op_sel_hi:[1,0]
	v_add_f32_e32 v61, v62, v63
	s_nop 1
	v_add_f32_dpp v61, v61, v61 quad_perm:[1,0,3,2] row_mask:0xf bank_mask:0xf
	s_nop 1
	v_add_f32_dpp v61, v61, v61 quad_perm:[2,3,0,1] row_mask:0xf bank_mask:0xf
	s_nop 1
	v_add_f32_dpp v61, v61, v61 row_half_mirror row_mask:0xf bank_mask:0xf
	s_nop 1
	v_add_f32_dpp v61, v61, v61 row_mirror row_mask:0xf bank_mask:0xf
	s_nop 1
	v_add_f32_dpp v61, v61, v61 row_bcast:15 row_mask:0xa bank_mask:0xf
	s_nop 1
	v_add_f32_dpp v61, v61, v61 row_bcast:31 row_mask:0xc bank_mask:0xf
	s_nop 1
	v_readlane_b32 s99, v61, 63
	s_nop 1
	v_mov_b32_e32 v78, s99
	v_pk_mul_f32 v[40:41], v[40:41], v[48:49] op_sel_hi:[1,0]
	s_lshl_b64 s[0:1], s[4:5], 11
	v_lshl_add_u64 v[62:63], v[50:51], 0, s[0:1]
	v_pk_mul_f32 v[46:47], v[46:47], v[48:49] op_sel_hi:[1,0]
	v_pk_mul_f32 v[64:65], v[2:3], v[42:43]
	v_pk_mul_f32 v[42:43], v[0:1], v[40:41]
	v_cvt_pk_bf16_f32 v40, v44, v45
	v_pk_mul_f32 v[46:47], v[6:7], v[46:47]
	v_cvt_pk_bf16_f32 v41, v46, v47
	v_cvt_pk_bf16_f32 v42, v42, v43
	v_cvt_pk_bf16_f32 v43, v64, v65
	global_store_dwordx4 v[62:63], v[40:43], off
	v_pk_mul_f32 v[36:37], v[36:37], v[48:49] op_sel_hi:[1,0]
	v_pk_mul_f32 v[34:35], v[34:35], v[48:49] op_sel_hi:[1,0]
	v_pk_mul_f32 v[36:37], v[12:13], v[36:37]
	v_pk_mul_f32 v[32:33], v[32:33], v[48:49] op_sel_hi:[1,0]
	v_pk_mul_f32 v[38:39], v[38:39], v[48:49] op_sel_hi:[1,0]
	v_pk_mul_f32 v[40:41], v[10:11], v[34:35]
	v_pk_mul_f32 v[34:35], v[8:9], v[32:33]
	v_cvt_pk_bf16_f32 v32, v36, v37
	v_pk_mul_f32 v[38:39], v[14:15], v[38:39]
	v_mov_b32_e32 v36, v78
	v_fmamk_f32 v36, v36, 0x3a800000, v60
	v_mul_f32_e32 v37, 0x4b800000, v36
	v_cmp_gt_f32_e64 s[0:1], s8, v36
	v_cvt_pk_bf16_f32 v33, v38, v39
	v_cvt_pk_bf16_f32 v34, v34, v35
	v_cvt_pk_bf16_f32 v35, v40, v41
	global_store_dwordx4 v[62:63], v[32:35], off offset:1024
	s_nop 0
	v_cndmask_b32_e64 v36, v36, v37, s[0:1]
	v_rsq_f32_e32 v36, v36
	s_nop 0
	v_mul_f32_e32 v32, 0x45800000, v36
	v_cndmask_b32_e64 v32, v36, v32, s[0:1]
	s_and_saveexec_b64 s[0:1], vcc
	s_cbranch_execz .LBB0_103
	s_lshl_b64 s[4:5], s[2:3], 2
	s_add_u32 s4, s6, s4
	s_addc_u32 s5, s7, s5
	global_store_dword v49, v32, s[4:5]
	s_branch .LBB0_103
